# D2: residual-base tile pulled toward L2/MALL during the K-loop, one wave per K-iteration (26+2w), two 128-byte lines per lane
# speedup vs baseline: 1.0013x; 1.0013x over previous
; template <class Epi, class Sched, bool ALIGN_EPI = false, bool SP2 = false>
; __device__ __forceinline__ void gemm_phase(PG8_LAS unsigned char* lds, const Gemm g, const Sched& S, const Epi& E) {
;     const int tid = threadIdx.x, wid = __builtin_amdgcn_readfirstlane(tid >> 6), lane = tid & 63, wr = wid >> 2, wc = wid & 3, fr = lane & 15, fq = lane >> 4;
;     const int K = g.K, nt = K / BK;
;     unsigned voffA[2], voffB[2];
; #pragma unroll
;     for (int i = 0; i < 2; ++i) { int R, C; stage_rc(tid * 16 + i * 8192, R, C); const int Rb = Epi::PERM ? ((R & ~31) + perm32(R & 31)) : R;
;         voffA[i] = (unsigned)(R * K + C) * 2u; voffB[i] = (unsigned)(Rb * K + C) * 2u; }
;     const size_t kstep = (size_t)(BK * 2);
;     const size_t hstep = (size_t)HALF * K * 2;
;     const size_t tstep = 2 * hstep;
;     const unsigned ldsw = (unsigned)wid * 1024u;
;     const int aoff = lds_byte(wr * 64 + fr, fq * 8), boff = lds_byte(wc * 32 + fr, fq * 8);
;     ...
;     Unit cur, nxt; int ui = 0;
;     if (!S.next(0, cur)) return;
; __global__ void __launch_bounds__(NTHREADS, 2) mega(Params P, int ph_lo, int ph_hi) {
;     ...
;     if (IN(13)) { pg8::Gemm g{(const bf16*)(ws + OFF_ACT), (const bf16*)(ws + OFF_WD2), MMAIN, DM, DFF}; pg8::StaticOrder S; S.init(MMAIN, DM, G, (int)blockIdx.x);
;         pg8::EpiResid E{nullptr, (const bf16*)(ws + OFF_HB2), nullptr, P.out, nullptr, nullptr, 0.5f}; pg8::gemm_phase<pg8::EpiResid, pg8::StaticOrder, true, true>(lds, g, S, E); }
.LBB0_1168:
	s_cmp_gt_i32 s88, 13
	s_cselect_b64 s[0:1], -1, 0
	s_cmp_lt_i32 s89, 14
	s_cselect_b64 s[2:3], -1, 0
	s_or_b64 s[0:1], s[0:1], s[2:3]
	s_and_b64 vcc, exec, s[0:1]
	s_cbranch_vccnz .LBB0_1199
	s_cmpk_gt_i32 s33, 0xff
	v_readfirstlane_b32 s2, v209
	v_lshrrev_b32_e32 v240, 1, v209
	v_and_b32_e32 v241, 1, v209
	v_lshlrev_b32_e32 v240, 11, v240
	v_lshl_add_u32 v240, v241, 8, v240
	s_lshr_b32 s101, s2, 6
	s_lshl_b32 s101, s101, 1
	s_add_i32 s101, s101, 26
	s_cbranch_scc1 .LBB0_1199
	s_ashr_i32 s22, s33, 31
	s_lshr_b32 s0, s22, 29
	s_add_i32 s5, s33, s0
	s_and_b32 s0, s5, -8
	s_sub_i32 s3, s33, s0
	s_cmp_gt_i32 s3, -1
	s_cbranch_scc0 .LBB0_1172
	s_lshl_b32 s4, s3, 5
	s_ashr_i32 s1, s5, 3
	s_cbranch_execz .LBB0_1173
	s_branch .LBB0_1174

; #define PG8_STAGE(bufoff, gbase, voff) do { _Pragma("unroll") for (int _i = 0; _i < 2; ++_i) \
;         __builtin_amdgcn_global_load_lds((const unsigned*)((const char*)(gbase) + (voff)[_i]), (PG8_LAS unsigned*)(lds + (bufoff) + ldsw + _i * 8192), 16, 0, 0); } while (0)
; #define PG8_LDA(dst, b, h) do { _Pragma("unroll") for (int m = 0; m < 4; ++m) _Pragma("unroll") for (int k = 0; k < 2; ++k) dst[m][k] = *(const PG8_LAS bf16x8*)(lds + PG8_SA(b, h) + aoff + m * 2048 + k * 1024); } while (0)
; #define PG8_LDB(dst, b, h) do { _Pragma("unroll") for (int n = 0; n < 2; ++n) _Pragma("unroll") for (int k = 0; k < 2; ++k) dst[n][k] = *(const PG8_LAS bf16x8*)(lds + PG8_SB(b, h) + boff + n * 2048 + k * 1024); } while (0)
; #define PG8_MMA(ai, bj, At, Bt) do { __builtin_amdgcn_s_setprio(1); _Pragma("unroll") for (int m = 0; m < 4; ++m) _Pragma("unroll") for (int n = 0; n < 2; ++n) _Pragma("unroll") for (int k = 0; k < 2; ++k) \
;         acc[ai][bj][m][n] = __builtin_amdgcn_mfma_f32_16x16x32_bf16(Bt[n][k], At[m][k], acc[ai][bj][m][n], 0, 0, 0); __builtin_amdgcn_s_setprio(0); } while (0)
; #define PG8_WAIT_V(n) asm volatile("s_waitcnt vmcnt(" #n ")" ::: "memory")
; #define PG8_WAIT_L(n) asm volatile("s_waitcnt lgkmcnt(" #n ")" ::: "memory")
; #define PG8_BAR __builtin_amdgcn_s_barrier()
; #define PG8_SCHED __builtin_amdgcn_sched_barrier(0)
; template <class Epi, class Sched, bool ALIGN_EPI = false, bool SP2 = false>
; __device__ __forceinline__ void gemm_phase(PG8_LAS unsigned char* lds, const Gemm g, const Sched& S, const Epi& E) {
;     ...
;             PG8_LDB(B0, 0, 0); PG8_LDB(B1, 0, 1); PG8_SCHED; PG8_LDA(At, 0, 0); PG8_STAGE(PG8_SA(1, 1), a1 + hstep, voffA);
;             PG8_WAIT_V(8); PG8_WAIT_L(0); PG8_BAR; PG8_MMA(0, 0, At, B0); PG8_MMA(0, 1, At, B1); PG8_BAR; PG8_SCHED;
;             PG8_LDA(At, 0, 1); PG8_STAGE(PG8_SB(0, 0), b2, voffB); PG8_STAGE(PG8_SB(0, 1), b2 + hstep, voffB); PG8_STAGE(PG8_SA(0, 0), a2, voffA);
;             PG8_WAIT_V(8); PG8_WAIT_L(0); PG8_BAR; PG8_MMA(1, 0, At, B0); PG8_MMA(1, 1, At, B1); PG8_BAR; PG8_SCHED;
.LBB0_1190:
	ds_read_b128 v[144:147], v151
	ds_read_b128 v[154:157], v151 offset:1024
	ds_read_b128 v[158:161], v151 offset:2048
	ds_read_b128 v[162:165], v151 offset:3072
	ds_read_b128 v[166:169], v152
	ds_read_b128 v[170:173], v152 offset:1024
	ds_read_b128 v[174:177], v152 offset:2048
	ds_read_b128 v[178:181], v152 offset:3072
	s_add_u32 s18, s16, 0xfff50080
	s_addc_u32 s19, s17, -1
	s_cmp_eq_u32 s46, 40
	s_cselect_b32 s21, s3, s19
	s_cselect_b32 s20, s2, s18
	s_cselect_b32 s19, s15, s45
	s_cselect_b32 s18, s14, s44
	v_lshl_add_u64 v[214:215], s[16:17], 0, v[136:137]
	s_add_i32 m0, s28, 0xc000
	ds_read_b128 v[182:185], v153
	ds_read_b128 v[186:189], v153 offset:1024
	ds_read_b128 v[190:193], v153 offset:2048
	ds_read_b128 v[194:197], v153 offset:3072
	ds_read_b128 v[198:201], v153 offset:4096
	ds_read_b128 v[202:205], v153 offset:5120
	ds_read_b128 v[206:209], v153 offset:6144
	ds_read_b128 v[210:213], v153 offset:7168
	global_load_lds_dwordx4 v[214:215], off
	v_lshl_add_u64 v[214:215], s[16:17], 0, v[138:139]
	s_add_i32 m0, s28, 0xe000
	s_nop 0
	global_load_lds_dwordx4 v[214:215], off
	s_waitcnt vmcnt(8)
	s_waitcnt lgkmcnt(0)
	s_barrier
	s_cmp_eq_u32 s46, s101
	s_cbranch_scc0 .Lmy_pf13_skip
	s_lshl_b32 s98, s42, 19
	s_lshl_b32 s99, s43, 9
	s_add_i32 s98, s98, s99
	v_add_u32_e32 v241, s98, v240
	s_add_u32 s98, s86, 0xb700000
	s_addc_u32 s99, s87, 0
	global_load_dword v242, v241, s[98:99]
	global_load_dword v242, v241, s[98:99] offset:128
.Lmy_pf13_skip:
	s_setprio 1
	s_waitcnt lgkmcnt(0)
	v_mfma_f32_16x16x32_bf16 v[124:127], v[144:147], v[182:185], v[124:127]
	v_mfma_f32_16x16x32_bf16 v[120:123], v[158:161], v[182:185], v[120:123]
	v_mfma_f32_16x16x32_bf16 v[108:111], v[144:147], v[190:193], v[108:111]
	v_mfma_f32_16x16x32_bf16 v[104:107], v[158:161], v[190:193], v[104:107]
	v_mfma_f32_16x16x32_bf16 v[92:95], v[144:147], v[198:201], v[92:95]
	v_mfma_f32_16x16x32_bf16 v[88:91], v[158:161], v[198:201], v[88:91]
	v_mfma_f32_16x16x32_bf16 v[76:79], v[144:147], v[206:209], v[76:79]
	v_mfma_f32_16x16x32_bf16 v[72:75], v[158:161], v[206:209], v[72:75]
	v_mfma_f32_16x16x32_bf16 v[124:127], v[154:157], v[186:189], v[124:127]
	v_mfma_f32_16x16x32_bf16 v[120:123], v[162:165], v[186:189], v[120:123]
	v_mfma_f32_16x16x32_bf16 v[108:111], v[154:157], v[194:197], v[108:111]
	v_mfma_f32_16x16x32_bf16 v[104:107], v[162:165], v[194:197], v[104:107]
	v_mfma_f32_16x16x32_bf16 v[92:95], v[154:157], v[202:205], v[92:95]
	v_mfma_f32_16x16x32_bf16 v[88:91], v[162:165], v[202:205], v[88:91]
	v_mfma_f32_16x16x32_bf16 v[76:79], v[154:157], v[210:213], v[76:79]
	v_mfma_f32_16x16x32_bf16 v[72:75], v[162:165], v[210:213], v[72:75]
	s_setprio 0
	s_setprio 1
	v_mfma_f32_16x16x32_bf16 v[116:119], v[166:169], v[182:185], v[116:119]
	v_mfma_f32_16x16x32_bf16 v[112:115], v[174:177], v[182:185], v[112:115]
	v_mfma_f32_16x16x32_bf16 v[100:103], v[166:169], v[190:193], v[100:103]
	v_mfma_f32_16x16x32_bf16 v[96:99], v[174:177], v[190:193], v[96:99]
	v_mfma_f32_16x16x32_bf16 v[84:87], v[166:169], v[198:201], v[84:87]
	v_mfma_f32_16x16x32_bf16 v[80:83], v[174:177], v[198:201], v[80:83]
	v_mfma_f32_16x16x32_bf16 v[68:71], v[166:169], v[206:209], v[68:71]
	v_mfma_f32_16x16x32_bf16 v[64:67], v[174:177], v[206:209], v[64:67]
	v_mfma_f32_16x16x32_bf16 v[116:119], v[170:173], v[186:189], v[116:119]
	v_mfma_f32_16x16x32_bf16 v[112:115], v[178:181], v[186:189], v[112:115]
	v_mfma_f32_16x16x32_bf16 v[100:103], v[170:173], v[194:197], v[100:103]
	v_mfma_f32_16x16x32_bf16 v[96:99], v[178:181], v[194:197], v[96:99]
	v_mfma_f32_16x16x32_bf16 v[84:87], v[170:173], v[202:205], v[84:87]
	v_mfma_f32_16x16x32_bf16 v[80:83], v[178:181], v[202:205], v[80:83]
	v_mfma_f32_16x16x32_bf16 v[68:71], v[170:173], v[210:213], v[68:71]
	v_mfma_f32_16x16x32_bf16 v[64:67], v[178:181], v[210:213], v[64:67]
	s_setprio 0
	s_barrier
	s_add_i32 s47, s38, s27
	v_lshl_add_u64 v[214:215], s[18:19], 0, v[130:131]
	s_mov_b32 m0, s47
	ds_read_b128 v[182:185], v153 offset:16384
	ds_read_b128 v[186:189], v153 offset:17408
	ds_read_b128 v[190:193], v153 offset:18432
	ds_read_b128 v[194:197], v153 offset:19456
	ds_read_b128 v[198:201], v153 offset:20480
	ds_read_b128 v[202:205], v153 offset:21504
	ds_read_b128 v[206:209], v153 offset:22528
	ds_read_b128 v[210:213], v153 offset:23552
	global_load_lds_dwordx4 v[214:215], off
	s_add_i32 m0, s47, 0x2000
	s_add_u32 s48, s18, 0xb0000
	v_lshl_add_u64 v[216:217], s[18:19], 0, v[134:135]
	s_addc_u32 s49, s19, 0
	s_add_i32 s47, s39, s27
	global_load_lds_dwordx4 v[216:217], off
	v_lshl_add_u64 v[218:219], s[48:49], 0, v[130:131]
	s_mov_b32 m0, s47
	v_lshl_add_u64 v[220:221], s[20:21], 0, v[132:133]
	global_load_lds_dwordx4 v[218:219], off
	v_lshl_add_u64 v[218:219], s[48:49], 0, v[134:135]
	s_add_i32 m0, s47, 0x2000
	s_nop 0
	global_load_lds_dwordx4 v[218:219], off
	v_lshl_add_u64 v[218:219], s[20:21], 0, v[128:129]
	s_mov_b32 m0, s28
	s_nop 0
	global_load_lds_dwordx4 v[218:219], off
	s_mov_b32 m0, s29
	s_nop 0
	global_load_lds_dwordx4 v[220:221], off
	s_waitcnt vmcnt(8)
	s_waitcnt lgkmcnt(0)
	s_barrier
; #define PG8_STAGE(bufoff, gbase, voff) do { _Pragma("unroll") for (int _i = 0; _i < 2; ++_i) \
;         __builtin_amdgcn_global_load_lds((const unsigned*)((const char*)(gbase) + (voff)[_i]), (PG8_LAS unsigned*)(lds + (bufoff) + ldsw + _i * 8192), 16, 0, 0); } while (0)
; #define PG8_LDA(dst, b, h) do { _Pragma("unroll") for (int m = 0; m < 4; ++m) _Pragma("unroll") for (int k = 0; k < 2; ++k) dst[m][k] = *(const PG8_LAS bf16x8*)(lds + PG8_SA(b, h) + aoff + m * 2048 + k * 1024); } while (0)
; #define PG8_LDB(dst, b, h) do { _Pragma("unroll") for (int n = 0; n < 2; ++n) _Pragma("unroll") for (int k = 0; k < 2; ++k) dst[n][k] = *(const PG8_LAS bf16x8*)(lds + PG8_SB(b, h) + boff + n * 2048 + k * 1024); } while (0)
; #define PG8_MMA(ai, bj, At, Bt) do { __builtin_amdgcn_s_setprio(1); _Pragma("unroll") for (int m = 0; m < 4; ++m) _Pragma("unroll") for (int n = 0; n < 2; ++n) _Pragma("unroll") for (int k = 0; k < 2; ++k) \
;         acc[ai][bj][m][n] = __builtin_amdgcn_mfma_f32_16x16x32_bf16(Bt[n][k], At[m][k], acc[ai][bj][m][n], 0, 0, 0); __builtin_amdgcn_s_setprio(0); } while (0)
; #define PG8_WAIT_V(n) asm volatile("s_waitcnt vmcnt(" #n ")" ::: "memory")
; #define PG8_WAIT_L(n) asm volatile("s_waitcnt lgkmcnt(" #n ")" ::: "memory")
; #define PG8_BAR __builtin_amdgcn_s_barrier()
; #define PG8_SCHED __builtin_amdgcn_sched_barrier(0)
; template <class Epi, class Sched, bool ALIGN_EPI = false, bool SP2 = false>
; __device__ __forceinline__ void gemm_phase(PG8_LAS unsigned char* lds, const Gemm g, const Sched& S, const Epi& E) {
;     ...
;             PG8_WAIT_V(8); PG8_WAIT_L(0); PG8_BAR; PG8_MMA(1, 0, At, B0); PG8_MMA(1, 1, At, B1); PG8_BAR; PG8_SCHED;
;             PG8_LDB(B0, 1, 0); PG8_LDB(B1, 1, 1); PG8_SCHED; PG8_LDA(At, 1, 0); PG8_STAGE(PG8_SA(0, 1), a2 + hstep, voffA);
;             PG8_WAIT_V(8); PG8_WAIT_L(0); PG8_BAR; PG8_MMA(0, 0, At, B0); PG8_MMA(0, 1, At, B1); PG8_BAR; PG8_SCHED;
	s_setprio 1
	s_waitcnt lgkmcnt(0)
	v_mfma_f32_16x16x32_bf16 v[60:63], v[144:147], v[182:185], v[60:63]
	v_mfma_f32_16x16x32_bf16 v[56:59], v[158:161], v[182:185], v[56:59]
	v_mfma_f32_16x16x32_bf16 v[44:47], v[144:147], v[190:193], v[44:47]
	v_mfma_f32_16x16x32_bf16 v[40:43], v[158:161], v[190:193], v[40:43]
	v_mfma_f32_16x16x32_bf16 v[28:31], v[144:147], v[198:201], v[28:31]
	v_mfma_f32_16x16x32_bf16 v[24:27], v[158:161], v[198:201], v[24:27]
	v_mfma_f32_16x16x32_bf16 v[12:15], v[144:147], v[206:209], v[12:15]
	v_mfma_f32_16x16x32_bf16 v[8:11], v[158:161], v[206:209], v[8:11]
	v_mfma_f32_16x16x32_bf16 v[60:63], v[154:157], v[186:189], v[60:63]
	v_mfma_f32_16x16x32_bf16 v[56:59], v[162:165], v[186:189], v[56:59]
	v_mfma_f32_16x16x32_bf16 v[44:47], v[154:157], v[194:197], v[44:47]
	v_mfma_f32_16x16x32_bf16 v[40:43], v[162:165], v[194:197], v[40:43]
	v_mfma_f32_16x16x32_bf16 v[28:31], v[154:157], v[202:205], v[28:31]
	v_mfma_f32_16x16x32_bf16 v[24:27], v[162:165], v[202:205], v[24:27]
	v_mfma_f32_16x16x32_bf16 v[12:15], v[154:157], v[210:213], v[12:15]
	v_mfma_f32_16x16x32_bf16 v[8:11], v[162:165], v[210:213], v[8:11]
	s_setprio 0
	s_setprio 1
	v_mfma_f32_16x16x32_bf16 v[52:55], v[166:169], v[182:185], v[52:55]
	v_mfma_f32_16x16x32_bf16 v[48:51], v[174:177], v[182:185], v[48:51]
	v_mfma_f32_16x16x32_bf16 v[36:39], v[166:169], v[190:193], v[36:39]
	v_mfma_f32_16x16x32_bf16 v[32:35], v[174:177], v[190:193], v[32:35]
	v_mfma_f32_16x16x32_bf16 v[20:23], v[166:169], v[198:201], v[20:23]
	v_mfma_f32_16x16x32_bf16 v[16:19], v[174:177], v[198:201], v[16:19]
	v_mfma_f32_16x16x32_bf16 v[4:7], v[166:169], v[206:209], v[4:7]
	v_mfma_f32_16x16x32_bf16 v[0:3], v[174:177], v[206:209], v[0:3]
	v_mfma_f32_16x16x32_bf16 v[52:55], v[170:173], v[186:189], v[52:55]
	v_mfma_f32_16x16x32_bf16 v[48:51], v[178:181], v[186:189], v[48:51]
	v_mfma_f32_16x16x32_bf16 v[36:39], v[170:173], v[194:197], v[36:39]
	v_mfma_f32_16x16x32_bf16 v[32:35], v[178:181], v[194:197], v[32:35]
	v_mfma_f32_16x16x32_bf16 v[20:23], v[170:173], v[202:205], v[20:23]
	v_mfma_f32_16x16x32_bf16 v[16:19], v[178:181], v[202:205], v[16:19]
	v_mfma_f32_16x16x32_bf16 v[4:7], v[170:173], v[210:213], v[4:7]
	v_mfma_f32_16x16x32_bf16 v[0:3], v[178:181], v[210:213], v[0:3]
	s_setprio 0
	s_barrier
	s_add_i32 s47, 0, 0x18000
	s_add_i32 s48, 0, 0x1c000
	v_add_u32_e32 v162, s47, v149
	v_add_u32_e32 v178, s48, v149
	ds_read_b128 v[144:147], v162
	ds_read_b128 v[154:157], v162 offset:1024
	ds_read_b128 v[158:161], v162 offset:2048
	ds_read_b128 v[162:165], v162 offset:3072
	ds_read_b128 v[166:169], v178
	ds_read_b128 v[170:173], v178 offset:1024
	ds_read_b128 v[174:177], v178 offset:2048
	ds_read_b128 v[178:181], v178 offset:3072
	s_add_u32 s20, s20, 0xb0000
	s_addc_u32 s21, s21, 0
	s_mov_b32 m0, s30
	v_lshl_add_u64 v[222:223], s[20:21], 0, v[128:129]
	ds_read_b128 v[182:185], v153 offset:32768
	ds_read_b128 v[186:189], v153 offset:33792
	ds_read_b128 v[190:193], v153 offset:34816
	ds_read_b128 v[194:197], v153 offset:35840
	ds_read_b128 v[198:201], v153 offset:36864
	ds_read_b128 v[202:205], v153 offset:37888
	ds_read_b128 v[206:209], v153 offset:38912
	ds_read_b128 v[210:213], v153 offset:39936
	global_load_lds_dwordx4 v[222:223], off
	v_lshl_add_u64 v[222:223], s[20:21], 0, v[132:133]
	s_mov_b32 m0, s31
	s_nop 0
	global_load_lds_dwordx4 v[222:223], off
	s_waitcnt vmcnt(8)
	s_waitcnt lgkmcnt(0)
	s_barrier
	s_setprio 1
	s_waitcnt lgkmcnt(0)
	v_mfma_f32_16x16x32_bf16 v[124:127], v[144:147], v[182:185], v[124:127]
	v_mfma_f32_16x16x32_bf16 v[120:123], v[158:161], v[182:185], v[120:123]
	v_mfma_f32_16x16x32_bf16 v[108:111], v[144:147], v[190:193], v[108:111]
	v_mfma_f32_16x16x32_bf16 v[104:107], v[158:161], v[190:193], v[104:107]
	v_mfma_f32_16x16x32_bf16 v[92:95], v[144:147], v[198:201], v[92:95]
	v_mfma_f32_16x16x32_bf16 v[88:91], v[158:161], v[198:201], v[88:91]
	v_mfma_f32_16x16x32_bf16 v[76:79], v[144:147], v[206:209], v[76:79]
	v_mfma_f32_16x16x32_bf16 v[72:75], v[158:161], v[206:209], v[72:75]
	v_mfma_f32_16x16x32_bf16 v[124:127], v[154:157], v[186:189], v[124:127]
	v_mfma_f32_16x16x32_bf16 v[120:123], v[162:165], v[186:189], v[120:123]
	v_mfma_f32_16x16x32_bf16 v[108:111], v[154:157], v[194:197], v[108:111]
	v_mfma_f32_16x16x32_bf16 v[104:107], v[162:165], v[194:197], v[104:107]
	v_mfma_f32_16x16x32_bf16 v[92:95], v[154:157], v[202:205], v[92:95]
	v_mfma_f32_16x16x32_bf16 v[88:91], v[162:165], v[202:205], v[88:91]
	v_mfma_f32_16x16x32_bf16 v[76:79], v[154:157], v[210:213], v[76:79]
	v_mfma_f32_16x16x32_bf16 v[72:75], v[162:165], v[210:213], v[72:75]
	s_setprio 0
	s_setprio 1
	v_mfma_f32_16x16x32_bf16 v[116:119], v[166:169], v[182:185], v[116:119]
	v_mfma_f32_16x16x32_bf16 v[112:115], v[174:177], v[182:185], v[112:115]
	v_mfma_f32_16x16x32_bf16 v[100:103], v[166:169], v[190:193], v[100:103]
	v_mfma_f32_16x16x32_bf16 v[96:99], v[174:177], v[190:193], v[96:99]
	v_mfma_f32_16x16x32_bf16 v[84:87], v[166:169], v[198:201], v[84:87]
	v_mfma_f32_16x16x32_bf16 v[80:83], v[174:177], v[198:201], v[80:83]
	v_mfma_f32_16x16x32_bf16 v[68:71], v[166:169], v[206:209], v[68:71]
	v_mfma_f32_16x16x32_bf16 v[64:67], v[174:177], v[206:209], v[64:67]
	v_mfma_f32_16x16x32_bf16 v[116:119], v[170:173], v[186:189], v[116:119]
	v_mfma_f32_16x16x32_bf16 v[112:115], v[178:181], v[186:189], v[112:115]
	v_mfma_f32_16x16x32_bf16 v[100:103], v[170:173], v[194:197], v[100:103]
	v_mfma_f32_16x16x32_bf16 v[96:99], v[178:181], v[194:197], v[96:99]
	v_mfma_f32_16x16x32_bf16 v[84:87], v[170:173], v[202:205], v[84:87]
	v_mfma_f32_16x16x32_bf16 v[80:83], v[178:181], v[202:205], v[80:83]
	v_mfma_f32_16x16x32_bf16 v[68:71], v[170:173], v[210:213], v[68:71]
	v_mfma_f32_16x16x32_bf16 v[64:67], v[178:181], v[210:213], v[64:67]
	s_setprio 0
	s_barrier
; #define PG8_STAGE(bufoff, gbase, voff) do { _Pragma("unroll") for (int _i = 0; _i < 2; ++_i) \
;         __builtin_amdgcn_global_load_lds((const unsigned*)((const char*)(gbase) + (voff)[_i]), (PG8_LAS unsigned*)(lds + (bufoff) + ldsw + _i * 8192), 16, 0, 0); } while (0)
; #define PG8_LDA(dst, b, h) do { _Pragma("unroll") for (int m = 0; m < 4; ++m) _Pragma("unroll") for (int k = 0; k < 2; ++k) dst[m][k] = *(const PG8_LAS bf16x8*)(lds + PG8_SA(b, h) + aoff + m * 2048 + k * 1024); } while (0)
; #define PG8_MMA(ai, bj, At, Bt) do { __builtin_amdgcn_s_setprio(1); _Pragma("unroll") for (int m = 0; m < 4; ++m) _Pragma("unroll") for (int n = 0; n < 2; ++n) _Pragma("unroll") for (int k = 0; k < 2; ++k) \
;         acc[ai][bj][m][n] = __builtin_amdgcn_mfma_f32_16x16x32_bf16(Bt[n][k], At[m][k], acc[ai][bj][m][n], 0, 0, 0); __builtin_amdgcn_s_setprio(0); } while (0)
; #define PG8_WAIT_V(n) asm volatile("s_waitcnt vmcnt(" #n ")" ::: "memory")
; #define PG8_WAIT_L(n) asm volatile("s_waitcnt lgkmcnt(" #n ")" ::: "memory")
; #define PG8_BAR __builtin_amdgcn_s_barrier()
; #define PG8_SCHED __builtin_amdgcn_sched_barrier(0)
; template <class Epi, class Sched, bool ALIGN_EPI = false, bool SP2 = false>
; __device__ __forceinline__ void gemm_phase(PG8_LAS unsigned char* lds, const Gemm g, const Sched& S, const Epi& E) {
;     ...
;             PG8_LDA(At, 1, 1); PG8_STAGE(PG8_SB(1, 0), b3, voffB); PG8_STAGE(PG8_SB(1, 1), b3 + hstep, voffB); PG8_STAGE(PG8_SA(1, 0), a3, voffA);
;             PG8_WAIT_V(8); PG8_WAIT_L(0); PG8_BAR; PG8_MMA(1, 0, At, B0); PG8_MMA(1, 1, At, B1); PG8_BAR; PG8_SCHED;
	s_add_i32 s20, s47, s27
	v_lshl_add_u64 v[214:215], v[214:215], 0, s[8:9]
	s_mov_b32 m0, s20
	ds_read_b128 v[182:185], v153 offset:49152
	ds_read_b128 v[186:189], v153 offset:50176
	ds_read_b128 v[190:193], v153 offset:51200
	ds_read_b128 v[194:197], v153 offset:52224
	ds_read_b128 v[198:201], v153 offset:53248
	ds_read_b128 v[202:205], v153 offset:54272
	ds_read_b128 v[206:209], v153 offset:55296
	ds_read_b128 v[210:213], v153 offset:56320
	global_load_lds_dwordx4 v[214:215], off
	s_add_i32 m0, s20, 0x2000
	s_add_u32 s18, s18, 0xb0080
	v_lshl_add_u64 v[214:215], v[216:217], 0, s[8:9]
	s_addc_u32 s19, s19, 0
	s_add_i32 s20, s48, s27
	global_load_lds_dwordx4 v[214:215], off
	v_lshl_add_u64 v[214:215], s[18:19], 0, v[130:131]
	s_mov_b32 m0, s20
	s_nop 0
	global_load_lds_dwordx4 v[214:215], off
	v_lshl_add_u64 v[214:215], s[18:19], 0, v[134:135]
	s_add_i32 m0, s20, 0x2000
	s_nop 0
	global_load_lds_dwordx4 v[214:215], off
	v_lshl_add_u64 v[214:215], v[218:219], 0, s[8:9]
	s_mov_b32 m0, s35
	s_nop 0
	global_load_lds_dwordx4 v[214:215], off
	v_lshl_add_u64 v[214:215], v[220:221], 0, s[8:9]
	s_mov_b32 m0, s36
	s_nop 0
	global_load_lds_dwordx4 v[214:215], off
	s_waitcnt vmcnt(8)
	s_waitcnt lgkmcnt(0)
	s_barrier
	s_setprio 1
	s_waitcnt lgkmcnt(0)
	v_mfma_f32_16x16x32_bf16 v[60:63], v[144:147], v[182:185], v[60:63]
	v_mfma_f32_16x16x32_bf16 v[56:59], v[158:161], v[182:185], v[56:59]
	v_mfma_f32_16x16x32_bf16 v[44:47], v[144:147], v[190:193], v[44:47]
	v_mfma_f32_16x16x32_bf16 v[40:43], v[158:161], v[190:193], v[40:43]
	v_mfma_f32_16x16x32_bf16 v[28:31], v[144:147], v[198:201], v[28:31]
	v_mfma_f32_16x16x32_bf16 v[24:27], v[158:161], v[198:201], v[24:27]
	v_mfma_f32_16x16x32_bf16 v[12:15], v[144:147], v[206:209], v[12:15]
	v_mfma_f32_16x16x32_bf16 v[8:11], v[158:161], v[206:209], v[8:11]
	v_mfma_f32_16x16x32_bf16 v[60:63], v[154:157], v[186:189], v[60:63]
	v_mfma_f32_16x16x32_bf16 v[56:59], v[162:165], v[186:189], v[56:59]
	v_mfma_f32_16x16x32_bf16 v[44:47], v[154:157], v[194:197], v[44:47]
	v_mfma_f32_16x16x32_bf16 v[40:43], v[162:165], v[194:197], v[40:43]
	v_mfma_f32_16x16x32_bf16 v[28:31], v[154:157], v[202:205], v[28:31]
	v_mfma_f32_16x16x32_bf16 v[24:27], v[162:165], v[202:205], v[24:27]
	v_mfma_f32_16x16x32_bf16 v[12:15], v[154:157], v[210:213], v[12:15]
	v_mfma_f32_16x16x32_bf16 v[8:11], v[162:165], v[210:213], v[8:11]
	s_setprio 0
	s_setprio 1
	v_mfma_f32_16x16x32_bf16 v[52:55], v[166:169], v[182:185], v[52:55]
	v_mfma_f32_16x16x32_bf16 v[48:51], v[174:177], v[182:185], v[48:51]
	v_mfma_f32_16x16x32_bf16 v[36:39], v[166:169], v[190:193], v[36:39]
	v_mfma_f32_16x16x32_bf16 v[32:35], v[174:177], v[190:193], v[32:35]
	v_mfma_f32_16x16x32_bf16 v[20:23], v[166:169], v[198:201], v[20:23]
	v_mfma_f32_16x16x32_bf16 v[16:19], v[174:177], v[198:201], v[16:19]
	v_mfma_f32_16x16x32_bf16 v[4:7], v[166:169], v[206:209], v[4:7]
	v_mfma_f32_16x16x32_bf16 v[0:3], v[174:177], v[206:209], v[0:3]
	v_mfma_f32_16x16x32_bf16 v[52:55], v[170:173], v[186:189], v[52:55]
	v_mfma_f32_16x16x32_bf16 v[48:51], v[178:181], v[186:189], v[48:51]
	v_mfma_f32_16x16x32_bf16 v[36:39], v[170:173], v[194:197], v[36:39]
	v_mfma_f32_16x16x32_bf16 v[32:35], v[178:181], v[194:197], v[32:35]
	v_mfma_f32_16x16x32_bf16 v[20:23], v[170:173], v[202:205], v[20:23]
	v_mfma_f32_16x16x32_bf16 v[16:19], v[178:181], v[202:205], v[16:19]
	v_mfma_f32_16x16x32_bf16 v[4:7], v[170:173], v[210:213], v[4:7]
	v_mfma_f32_16x16x32_bf16 v[0:3], v[178:181], v[210:213], v[0:3]
	s_setprio 0
	s_barrier
	s_add_i32 s46, s46, 2
	s_add_u32 s16, s16, 0x100
	s_addc_u32 s17, s17, 0
	s_add_u32 s44, s44, 0x100
	s_addc_u32 s45, s45, 0
	s_cmp_gt_u32 s46, 41
	s_cbranch_scc0 .LBB0_1190
	s_and_b64 vcc, exec, s[10:11]
	s_cbranch_vccz .LBB0_1193
	s_barrier
